# in-proj GEMM: first K-iteration peeled, accumulators start from srcC=0 in their first MFMA; the 64 v_mov_b64 clear per tile removed
# speedup vs baseline: 1.0044x; 1.0044x over previous
; #define PG8_STAGE(bufoff, gbase, voff) do { _Pragma("unroll") for (int _i = 0; _i < 2; ++_i) \
;         __builtin_amdgcn_global_load_lds((const unsigned*)((const char*)(gbase) + (voff)[_i]), (LAS unsigned*)(lds + (bufoff) + ldsw + _i * 8192), 16, 0, 0); } while (0)
; #define PG8_LDA(dst, b, h) do { _Pragma("unroll") for (int m = 0; m < 4; ++m) _Pragma("unroll") for (int k = 0; k < 2; ++k) dst[m][k] = *(const LAS bf16x8*)(lds + PG8_SA(b, h) + aoff + m * 2048 + k * 1024); } while (0)
; #define PG8_LDB(dst, b, h) do { _Pragma("unroll") for (int n = 0; n < 2; ++n) _Pragma("unroll") for (int k = 0; k < 2; ++k) dst[n][k] = *(const LAS bf16x8*)(lds + PG8_SB(b, h) + boff + n * 2048 + k * 1024); } while (0)
; #define PG8_MMA(ai, bj, At, Bt) do { __builtin_amdgcn_s_setprio(1); _Pragma("unroll") for (int m = 0; m < 4; ++m) _Pragma("unroll") for (int n = 0; n < 2; ++n) _Pragma("unroll") for (int k = 0; k < 2; ++k) \
;         acc[ai][bj][m][n] = __builtin_amdgcn_mfma_f32_16x16x32_bf16(Bt[n][k], At[m][k], acc[ai][bj][m][n], 0, 0, 0); __builtin_amdgcn_s_setprio(0); } while (0)
; #define PG8_WAIT_L(n) asm volatile("s_waitcnt lgkmcnt(" #n ")" ::: "memory")
; #define PG8_BAR __builtin_amdgcn_s_barrier()
; #define PG8_SCHED __builtin_amdgcn_sched_barrier(0)
; template <class Epi>
; DI void gemm_phase(LAS unsigned char* lds, const Gemm g, const StaticOrder& S, const Epi& E, const int tid) {
;     ...
;         const bool has_next = S.next(ui + 1, nxt);
;         const char* nA = has_next ? (const char*)g.A + (size_t)nxt.pm * tstepA : cA; const char* nB = has_next ? (const char*)g.Bt + (size_t)nxt.pn * tstepB : cB;
;         for (int t = 0; t < nt; t += 2) {
;             const bool last = (t == nt - 2);
;             const char* a1 = cA + PG8_KTA(t + 1);
;             const char* a2 = last ? nA : cA + PG8_KTA(t + 2); const char* b2 = last ? nB : cB + (size_t)(t + 2) * kstep;
;             const char* a3 = last ? nA + PG8_KTA(1) : cA + PG8_KTA(t + 3); const char* b3 = b2 + kstep;
;             PG8_LDB(B0, 0, 0); PG8_SCHED; PG8_LDA(At, 0, 0); PG8_STAGE(PG8_SA(1, 1), a1 + hstepA, voffA);
;             PG8_WAIT_L(8); PG8_BAR; PG8_WAIT_L(0); PG8_MMA(0, 0, At, B0); PG8_BAR; PG8_SCHED;
;             PG8_LDB(B1, 0, 1); PG8_STAGE(PG8_SB(0, 0), b2, voffB);
;             PG8_BAR; PG8_WAIT_L(0); PG8_MMA(0, 1, At, B1); PG8_BAR;
;             PG8_LDA(At, 0, 1); PG8_STAGE(PG8_SA(0, 0), a2, voffA);
.LBB0_61:
	s_ashr_i32 s43, s42, 31
	v_cmp_lt_i64_e32 vcc, s[6:7], v[142:143]
	s_lshl_b64 s[6:7], s[42:43], 20
	s_add_u32 s46, s70, s6
	s_addc_u32 s47, s71, s7
	s_and_b64 s[6:7], vcc, exec
	s_cselect_b32 s30, s47, s45
	s_cselect_b32 s31, s46, s44
	s_ashr_i32 s39, s38, 31
	s_lshl_b64 s[6:7], s[38:39], 20
	s_add_u32 s48, s36, s6
	s_addc_u32 s49, s37, s7
	s_and_b64 s[6:7], vcc, exec
	s_cselect_b32 s39, s49, s5
	s_cselect_b32 s43, s48, s4
	s_add_u32 s64, s31, 0x80
	s_addc_u32 s65, s30, 0
	s_add_u32 s6, s44, 0x80080
	s_addc_u32 s7, s45, 0
	s_add_u32 s66, s4, 0x100
	s_addc_u32 s67, s5, 0
	s_mov_b32 s68, -2
	s_mov_b64 s[4:5], 0
	v_lshl_add_u64 v[144:145], s[6:7], 0, v[138:139]
	v_lshl_add_u64 v[146:147], s[6:7], 0, v[140:141]
	s_add_u32 s6, s44, s4
	s_addc_u32 s7, s45, s5
	s_add_u32 s8, s6, 0x100
	s_addc_u32 s9, s7, 0
	s_add_u32 s69, s66, s4
	s_addc_u32 s78, s67, s5
	s_add_u32 s86, s6, 0x180
	s_addc_u32 s87, s7, 0
	s_cmpk_eq_i32 s4, 0xf00
	s_cselect_b32 s51, s30, s9
	s_cselect_b32 s50, s31, s8
	s_cselect_b32 s7, s39, s78
	s_cselect_b32 s6, s43, s69
	s_cselect_b32 s9, s65, s87
	s_cselect_b32 s8, s64, s86
	s_add_u32 s86, s44, s4
	s_addc_u32 s87, s45, s5
	s_add_u32 s86, s86, 0x80080
	s_addc_u32 s87, s87, 0
	v_add_u32_e32 v241, 0x10000, v150
	v_add_u32_e32 v242, 0x14000, v150
	v_add_u32_e32 v243, 0x18000, v150
	v_add_u32_e32 v244, 0x1c000, v150
	s_add_i32 s69, 0, 0x10000
	ds_read_b128 v[158:161], v241
	ds_read_b128 v[162:165], v241 offset:1024
	ds_read_b128 v[166:169], v241 offset:2048
	ds_read_b128 v[178:181], v241 offset:3072
	s_add_i32 m0, s41, 0xc000
	ds_read_b128 v[182:185], v151
	ds_read_b128 v[186:189], v151 offset:1024
	ds_read_b128 v[190:193], v151 offset:2048
	ds_read_b128 v[194:197], v151 offset:3072
	ds_read_b128 v[198:201], v151 offset:4096
	ds_read_b128 v[202:205], v151 offset:5120
	ds_read_b128 v[206:209], v151 offset:6144
	ds_read_b128 v[210:213], v151 offset:7168
	global_load_lds_dwordx4 v138, s[86:87]
	s_add_i32 m0, s41, 0xe000
	s_nop 0
	global_load_lds_dwordx4 v140, s[86:87]
	s_waitcnt lgkmcnt(8)
	s_barrier
	s_waitcnt lgkmcnt(0)
	s_setprio 1
	s_waitcnt lgkmcnt(0)
	v_mfma_f32_16x16x32_bf16 v[126:129], v[158:161], v[182:185], 0
	v_mfma_f32_16x16x32_bf16 v[122:125], v[166:169], v[182:185], 0
	v_mfma_f32_16x16x32_bf16 v[118:121], v[158:161], v[190:193], 0
	v_mfma_f32_16x16x32_bf16 v[114:117], v[166:169], v[190:193], 0
	v_mfma_f32_16x16x32_bf16 v[102:105], v[158:161], v[198:201], 0
	v_mfma_f32_16x16x32_bf16 v[98:101], v[166:169], v[198:201], 0
	v_mfma_f32_16x16x32_bf16 v[86:89], v[158:161], v[206:209], 0
	v_mfma_f32_16x16x32_bf16 v[82:85], v[166:169], v[206:209], 0
	v_mfma_f32_16x16x32_bf16 v[126:129], v[162:165], v[186:189], v[126:129]
	v_mfma_f32_16x16x32_bf16 v[122:125], v[178:181], v[186:189], v[122:125]
	v_mfma_f32_16x16x32_bf16 v[118:121], v[162:165], v[194:197], v[118:121]
	v_mfma_f32_16x16x32_bf16 v[114:117], v[178:181], v[194:197], v[114:117]
	v_mfma_f32_16x16x32_bf16 v[102:105], v[162:165], v[202:205], v[102:105]
	v_mfma_f32_16x16x32_bf16 v[98:101], v[178:181], v[202:205], v[98:101]
	v_mfma_f32_16x16x32_bf16 v[86:89], v[162:165], v[210:213], v[86:89]
	v_mfma_f32_16x16x32_bf16 v[82:85], v[178:181], v[210:213], v[82:85]
	s_setprio 0
	s_barrier
	s_add_i32 s78, 0, 0x14000
	s_add_i32 s69, s69, s26
	ds_read_b128 v[214:217], v242
	ds_read_b128 v[218:221], v242 offset:1024
	ds_read_b128 v[222:225], v242 offset:2048
	ds_read_b128 v[226:229], v242 offset:3072
	s_mov_b32 m0, s69
	s_nop 0
	global_load_lds_dwordx4 v0, s[6:7]
	s_add_i32 m0, s69, 0x2000
	s_nop 0
	global_load_lds_dwordx4 v130, s[6:7]
	s_barrier
	s_waitcnt lgkmcnt(0)
	s_setprio 1
	s_waitcnt lgkmcnt(0)
	v_mfma_f32_16x16x32_bf16 v[110:113], v[214:217], v[182:185], 0
	v_mfma_f32_16x16x32_bf16 v[106:109], v[222:225], v[182:185], 0
	v_mfma_f32_16x16x32_bf16 v[94:97], v[214:217], v[190:193], 0
	v_mfma_f32_16x16x32_bf16 v[90:93], v[222:225], v[190:193], 0
	v_mfma_f32_16x16x32_bf16 v[78:81], v[214:217], v[198:201], 0
	v_mfma_f32_16x16x32_bf16 v[74:77], v[222:225], v[198:201], 0
	v_mfma_f32_16x16x32_bf16 v[70:73], v[214:217], v[206:209], 0
	v_mfma_f32_16x16x32_bf16 v[66:69], v[222:225], v[206:209], 0
	v_mfma_f32_16x16x32_bf16 v[110:113], v[218:221], v[186:189], v[110:113]
	v_mfma_f32_16x16x32_bf16 v[106:109], v[226:229], v[186:189], v[106:109]
	v_mfma_f32_16x16x32_bf16 v[94:97], v[218:221], v[194:197], v[94:97]
	v_mfma_f32_16x16x32_bf16 v[90:93], v[226:229], v[194:197], v[90:93]
	v_mfma_f32_16x16x32_bf16 v[78:81], v[218:221], v[202:205], v[78:81]
	v_mfma_f32_16x16x32_bf16 v[74:77], v[226:229], v[202:205], v[74:77]
	v_mfma_f32_16x16x32_bf16 v[70:73], v[218:221], v[210:213], v[70:73]
	v_mfma_f32_16x16x32_bf16 v[66:69], v[226:229], v[210:213], v[66:69]
	s_setprio 0
	s_mov_b32 m0, s41
	s_barrier
	ds_read_b128 v[182:185], v151 offset:16384
	ds_read_b128 v[186:189], v151 offset:17408
	ds_read_b128 v[190:193], v151 offset:18432
	ds_read_b128 v[194:197], v151 offset:19456
	ds_read_b128 v[198:201], v151 offset:20480
	ds_read_b128 v[202:205], v151 offset:21504
	ds_read_b128 v[206:209], v151 offset:22528
	ds_read_b128 v[210:213], v151 offset:23552
	global_load_lds_dwordx4 v134, s[50:51]
	s_mov_b32 m0, s55
	s_nop 0
	global_load_lds_dwordx4 v132, s[50:51]
	s_barrier
; #define PG8_STAGE(bufoff, gbase, voff) do { _Pragma("unroll") for (int _i = 0; _i < 2; ++_i) \
;         __builtin_amdgcn_global_load_lds((const unsigned*)((const char*)(gbase) + (voff)[_i]), (LAS unsigned*)(lds + (bufoff) + ldsw + _i * 8192), 16, 0, 0); } while (0)
; #define PG8_LDA(dst, b, h) do { _Pragma("unroll") for (int m = 0; m < 4; ++m) _Pragma("unroll") for (int k = 0; k < 2; ++k) dst[m][k] = *(const LAS bf16x8*)(lds + PG8_SA(b, h) + aoff + m * 2048 + k * 1024); } while (0)
; #define PG8_LDB(dst, b, h) do { _Pragma("unroll") for (int n = 0; n < 2; ++n) _Pragma("unroll") for (int k = 0; k < 2; ++k) dst[n][k] = *(const LAS bf16x8*)(lds + PG8_SB(b, h) + boff + n * 2048 + k * 1024); } while (0)
; #define PG8_MMA(ai, bj, At, Bt) do { __builtin_amdgcn_s_setprio(1); _Pragma("unroll") for (int m = 0; m < 4; ++m) _Pragma("unroll") for (int n = 0; n < 2; ++n) _Pragma("unroll") for (int k = 0; k < 2; ++k) \
;         acc[ai][bj][m][n] = __builtin_amdgcn_mfma_f32_16x16x32_bf16(Bt[n][k], At[m][k], acc[ai][bj][m][n], 0, 0, 0); __builtin_amdgcn_s_setprio(0); } while (0)
; #define PG8_WAIT_V(n) asm volatile("s_waitcnt vmcnt(" #n ")" ::: "memory")
; #define PG8_WAIT_L(n) asm volatile("s_waitcnt lgkmcnt(" #n ")" ::: "memory")
; #define PG8_BAR __builtin_amdgcn_s_barrier()
; #define PG8_SCHED __builtin_amdgcn_sched_barrier(0)
; template <class Epi>
; DI void gemm_phase(LAS unsigned char* lds, const Gemm g, const StaticOrder& S, const Epi& E, const int tid) {
;     ...
;             PG8_BAR; PG8_WAIT_L(0); PG8_MMA(1, 0, At, B0); PG8_BAR; PG8_SCHED;
;             PG8_STAGE(PG8_SB(0, 1), b2 + hstepB, voffB);
;             PG8_WAIT_V(6); PG8_BAR; PG8_MMA(1, 1, At, B1); PG8_BAR;
;             PG8_LDB(B0, 1, 0); PG8_SCHED; PG8_LDA(At, 1, 0); PG8_STAGE(PG8_SA(0, 1), a2 + hstepA, voffA);
;             PG8_WAIT_L(8); PG8_BAR; PG8_WAIT_L(0); PG8_MMA(0, 0, At, B0); PG8_BAR; PG8_SCHED;
;             PG8_LDB(B1, 1, 1); PG8_STAGE(PG8_SB(1, 0), b3, voffB);
	s_waitcnt lgkmcnt(0)
	s_setprio 1
	s_waitcnt lgkmcnt(0)
	v_mfma_f32_16x16x32_bf16 v[62:65], v[158:161], v[182:185], 0
	v_mfma_f32_16x16x32_bf16 v[58:61], v[166:169], v[182:185], 0
	v_mfma_f32_16x16x32_bf16 v[54:57], v[158:161], v[190:193], 0
	v_mfma_f32_16x16x32_bf16 v[50:53], v[166:169], v[190:193], 0
	v_mfma_f32_16x16x32_bf16 v[38:41], v[158:161], v[198:201], 0
	v_mfma_f32_16x16x32_bf16 v[34:37], v[166:169], v[198:201], 0
	v_mfma_f32_16x16x32_bf16 v[22:25], v[158:161], v[206:209], 0
	v_mfma_f32_16x16x32_bf16 v[18:21], v[166:169], v[206:209], 0
	v_mfma_f32_16x16x32_bf16 v[62:65], v[162:165], v[186:189], v[62:65]
	v_mfma_f32_16x16x32_bf16 v[58:61], v[178:181], v[186:189], v[58:61]
	v_mfma_f32_16x16x32_bf16 v[54:57], v[162:165], v[194:197], v[54:57]
	v_mfma_f32_16x16x32_bf16 v[50:53], v[178:181], v[194:197], v[50:53]
	v_mfma_f32_16x16x32_bf16 v[38:41], v[162:165], v[202:205], v[38:41]
	v_mfma_f32_16x16x32_bf16 v[34:37], v[178:181], v[202:205], v[34:37]
	v_mfma_f32_16x16x32_bf16 v[22:25], v[162:165], v[210:213], v[22:25]
	v_mfma_f32_16x16x32_bf16 v[18:21], v[178:181], v[210:213], v[18:21]
	s_setprio 0
	s_barrier
	s_add_u32 s86, s6, 0x80000
	s_addc_u32 s87, s7, 0
	s_add_i32 s69, s78, s26
	s_mov_b32 m0, s69
	s_nop 0
	global_load_lds_dwordx4 v0, s[86:87]
	s_add_i32 m0, s69, 0x2000
	s_nop 0
	global_load_lds_dwordx4 v130, s[86:87]
	s_waitcnt vmcnt(6)
	s_barrier
	s_setprio 1
	v_mfma_f32_16x16x32_bf16 v[46:49], v[214:217], v[182:185], 0
	v_mfma_f32_16x16x32_bf16 v[42:45], v[222:225], v[182:185], 0
	v_mfma_f32_16x16x32_bf16 v[30:33], v[214:217], v[190:193], 0
	v_mfma_f32_16x16x32_bf16 v[26:29], v[222:225], v[190:193], 0
	v_mfma_f32_16x16x32_bf16 v[14:17], v[214:217], v[198:201], 0
	v_mfma_f32_16x16x32_bf16 v[10:13], v[222:225], v[198:201], 0
	v_mfma_f32_16x16x32_bf16 v[6:9], v[214:217], v[206:209], 0
	v_mfma_f32_16x16x32_bf16 v[2:5], v[222:225], v[206:209], 0
	v_mfma_f32_16x16x32_bf16 v[46:49], v[218:221], v[186:189], v[46:49]
	v_mfma_f32_16x16x32_bf16 v[42:45], v[226:229], v[186:189], v[42:45]
	v_mfma_f32_16x16x32_bf16 v[30:33], v[218:221], v[194:197], v[30:33]
	v_mfma_f32_16x16x32_bf16 v[26:29], v[226:229], v[194:197], v[26:29]
	v_mfma_f32_16x16x32_bf16 v[14:17], v[218:221], v[202:205], v[14:17]
	v_mfma_f32_16x16x32_bf16 v[10:13], v[226:229], v[202:205], v[10:13]
	v_mfma_f32_16x16x32_bf16 v[6:9], v[218:221], v[210:213], v[6:9]
	v_mfma_f32_16x16x32_bf16 v[2:5], v[226:229], v[210:213], v[2:5]
	s_setprio 0
	s_add_i32 s69, 0, 0x18000
	s_barrier
	ds_read_b128 v[158:161], v243
	ds_read_b128 v[162:165], v243 offset:1024
	ds_read_b128 v[166:169], v243 offset:2048
	ds_read_b128 v[178:181], v243 offset:3072
	s_add_u32 s50, s50, 0x80000
	s_addc_u32 s51, s51, 0
	s_mov_b32 m0, s56
	s_nop 0
	ds_read_b128 v[182:185], v151 offset:32768
	ds_read_b128 v[186:189], v151 offset:33792
	ds_read_b128 v[190:193], v151 offset:34816
	ds_read_b128 v[194:197], v151 offset:35840
	ds_read_b128 v[198:201], v151 offset:36864
	ds_read_b128 v[202:205], v151 offset:37888
	ds_read_b128 v[206:209], v151 offset:38912
	ds_read_b128 v[210:213], v151 offset:39936
	global_load_lds_dwordx4 v134, s[50:51]
	s_mov_b32 m0, s57
	s_nop 0
	global_load_lds_dwordx4 v132, s[50:51]
	s_waitcnt lgkmcnt(8)
	s_barrier
	s_waitcnt lgkmcnt(0)
	s_setprio 1
	s_waitcnt lgkmcnt(0)
	v_mfma_f32_16x16x32_bf16 v[126:129], v[158:161], v[182:185], v[126:129]
	v_mfma_f32_16x16x32_bf16 v[122:125], v[166:169], v[182:185], v[122:125]
	v_mfma_f32_16x16x32_bf16 v[118:121], v[158:161], v[190:193], v[118:121]
	v_mfma_f32_16x16x32_bf16 v[114:117], v[166:169], v[190:193], v[114:117]
	v_mfma_f32_16x16x32_bf16 v[102:105], v[158:161], v[198:201], v[102:105]
	v_mfma_f32_16x16x32_bf16 v[98:101], v[166:169], v[198:201], v[98:101]
	v_mfma_f32_16x16x32_bf16 v[86:89], v[158:161], v[206:209], v[86:89]
	v_mfma_f32_16x16x32_bf16 v[82:85], v[166:169], v[206:209], v[82:85]
	v_mfma_f32_16x16x32_bf16 v[126:129], v[162:165], v[186:189], v[126:129]
	v_mfma_f32_16x16x32_bf16 v[122:125], v[178:181], v[186:189], v[122:125]
	v_mfma_f32_16x16x32_bf16 v[118:121], v[162:165], v[194:197], v[118:121]
	v_mfma_f32_16x16x32_bf16 v[114:117], v[178:181], v[194:197], v[114:117]
	v_mfma_f32_16x16x32_bf16 v[102:105], v[162:165], v[202:205], v[102:105]
	v_mfma_f32_16x16x32_bf16 v[98:101], v[178:181], v[202:205], v[98:101]
	v_mfma_f32_16x16x32_bf16 v[86:89], v[162:165], v[210:213], v[86:89]
	v_mfma_f32_16x16x32_bf16 v[82:85], v[178:181], v[210:213], v[82:85]
	s_setprio 0
	s_barrier
	s_add_i32 s50, 0, 0x1c000
	s_add_i32 s51, s69, s26
	s_add_u32 s86, s6, s84
	s_addc_u32 s87, s7, s85
	s_mov_b32 m0, s51
	ds_read_b128 v[214:217], v244
	ds_read_b128 v[218:221], v244 offset:1024
	ds_read_b128 v[222:225], v244 offset:2048
	ds_read_b128 v[226:229], v244 offset:3072
	global_load_lds_dwordx4 v0, s[86:87]
	s_add_i32 m0, s51, 0x2000
	s_nop 0
	global_load_lds_dwordx4 v130, s[86:87]
	s_barrier
; #define PG8_STAGE(bufoff, gbase, voff) do { _Pragma("unroll") for (int _i = 0; _i < 2; ++_i) \
;         __builtin_amdgcn_global_load_lds((const unsigned*)((const char*)(gbase) + (voff)[_i]), (LAS unsigned*)(lds + (bufoff) + ldsw + _i * 8192), 16, 0, 0); } while (0)
; #define PG8_LDA(dst, b, h) do { _Pragma("unroll") for (int m = 0; m < 4; ++m) _Pragma("unroll") for (int k = 0; k < 2; ++k) dst[m][k] = *(const LAS bf16x8*)(lds + PG8_SA(b, h) + aoff + m * 2048 + k * 1024); } while (0)
; #define PG8_MMA(ai, bj, At, Bt) do { __builtin_amdgcn_s_setprio(1); _Pragma("unroll") for (int m = 0; m < 4; ++m) _Pragma("unroll") for (int n = 0; n < 2; ++n) _Pragma("unroll") for (int k = 0; k < 2; ++k) \
;         acc[ai][bj][m][n] = __builtin_amdgcn_mfma_f32_16x16x32_bf16(Bt[n][k], At[m][k], acc[ai][bj][m][n], 0, 0, 0); __builtin_amdgcn_s_setprio(0); } while (0)
; #define PG8_WAIT_V(n) asm volatile("s_waitcnt vmcnt(" #n ")" ::: "memory")
; #define PG8_WAIT_L(n) asm volatile("s_waitcnt lgkmcnt(" #n ")" ::: "memory")
; #define PG8_BAR __builtin_amdgcn_s_barrier()
; #define PG8_SCHED __builtin_amdgcn_sched_barrier(0)
; template <class Epi>
; DI void gemm_phase(LAS unsigned char* lds, const Gemm g, const StaticOrder& S, const Epi& E, const int tid) {
;     ...
;             const bool last = (t == nt - 2);
;             const char* a1 = cA + PG8_KTA(t + 1);
;             const char* a2 = last ? nA : cA + PG8_KTA(t + 2); const char* b2 = last ? nB : cB + (size_t)(t + 2) * kstep;
;             const char* a3 = last ? nA + PG8_KTA(1) : cA + PG8_KTA(t + 3); const char* b3 = b2 + kstep;
;     ...
;             PG8_BAR; PG8_WAIT_L(0); PG8_MMA(0, 1, At, B1); PG8_BAR;
;             PG8_LDA(At, 1, 1); PG8_STAGE(PG8_SA(1, 0), a3, voffA);
;             PG8_BAR; PG8_WAIT_L(0); PG8_MMA(1, 0, At, B0); PG8_BAR; PG8_SCHED;
;             PG8_STAGE(PG8_SB(1, 1), b3 + hstepB, voffB);
;             PG8_WAIT_V(6); PG8_BAR; PG8_MMA(1, 1, At, B1); PG8_BAR;
	s_waitcnt lgkmcnt(0)
	s_setprio 1
	s_waitcnt lgkmcnt(0)
	v_mfma_f32_16x16x32_bf16 v[110:113], v[214:217], v[182:185], v[110:113]
	v_mfma_f32_16x16x32_bf16 v[106:109], v[222:225], v[182:185], v[106:109]
	v_mfma_f32_16x16x32_bf16 v[94:97], v[214:217], v[190:193], v[94:97]
	v_mfma_f32_16x16x32_bf16 v[90:93], v[222:225], v[190:193], v[90:93]
	v_mfma_f32_16x16x32_bf16 v[78:81], v[214:217], v[198:201], v[78:81]
	v_mfma_f32_16x16x32_bf16 v[74:77], v[222:225], v[198:201], v[74:77]
	v_mfma_f32_16x16x32_bf16 v[70:73], v[214:217], v[206:209], v[70:73]
	v_mfma_f32_16x16x32_bf16 v[66:69], v[222:225], v[206:209], v[66:69]
	v_mfma_f32_16x16x32_bf16 v[110:113], v[218:221], v[186:189], v[110:113]
	v_mfma_f32_16x16x32_bf16 v[106:109], v[226:229], v[186:189], v[106:109]
	v_mfma_f32_16x16x32_bf16 v[94:97], v[218:221], v[194:197], v[94:97]
	v_mfma_f32_16x16x32_bf16 v[90:93], v[226:229], v[194:197], v[90:93]
	v_mfma_f32_16x16x32_bf16 v[78:81], v[218:221], v[202:205], v[78:81]
	v_mfma_f32_16x16x32_bf16 v[74:77], v[226:229], v[202:205], v[74:77]
	v_mfma_f32_16x16x32_bf16 v[70:73], v[218:221], v[210:213], v[70:73]
	v_mfma_f32_16x16x32_bf16 v[66:69], v[226:229], v[210:213], v[66:69]
	s_setprio 0
	s_mov_b32 m0, s59
	s_nop 0
	s_barrier
	ds_read_b128 v[182:185], v151 offset:49152
	ds_read_b128 v[186:189], v151 offset:50176
	ds_read_b128 v[190:193], v151 offset:51200
	ds_read_b128 v[194:197], v151 offset:52224
	ds_read_b128 v[198:201], v151 offset:53248
	ds_read_b128 v[202:205], v151 offset:54272
	ds_read_b128 v[206:209], v151 offset:55296
	ds_read_b128 v[210:213], v151 offset:56320
	global_load_lds_dwordx4 v134, s[8:9]
	s_mov_b32 m0, s60
	s_nop 0
	global_load_lds_dwordx4 v132, s[8:9]
	s_barrier
	s_waitcnt lgkmcnt(0)
	s_setprio 1
	s_waitcnt lgkmcnt(0)
	v_mfma_f32_16x16x32_bf16 v[62:65], v[158:161], v[182:185], v[62:65]
	v_mfma_f32_16x16x32_bf16 v[58:61], v[166:169], v[182:185], v[58:61]
	v_mfma_f32_16x16x32_bf16 v[54:57], v[158:161], v[190:193], v[54:57]
	v_mfma_f32_16x16x32_bf16 v[50:53], v[166:169], v[190:193], v[50:53]
	v_mfma_f32_16x16x32_bf16 v[38:41], v[158:161], v[198:201], v[38:41]
	v_mfma_f32_16x16x32_bf16 v[34:37], v[166:169], v[198:201], v[34:37]
	v_mfma_f32_16x16x32_bf16 v[22:25], v[158:161], v[206:209], v[22:25]
	v_mfma_f32_16x16x32_bf16 v[18:21], v[166:169], v[206:209], v[18:21]
	v_mfma_f32_16x16x32_bf16 v[62:65], v[162:165], v[186:189], v[62:65]
	v_mfma_f32_16x16x32_bf16 v[58:61], v[178:181], v[186:189], v[58:61]
	v_mfma_f32_16x16x32_bf16 v[54:57], v[162:165], v[194:197], v[54:57]
	v_mfma_f32_16x16x32_bf16 v[50:53], v[178:181], v[194:197], v[50:53]
	v_mfma_f32_16x16x32_bf16 v[38:41], v[162:165], v[202:205], v[38:41]
	v_mfma_f32_16x16x32_bf16 v[34:37], v[178:181], v[202:205], v[34:37]
	v_mfma_f32_16x16x32_bf16 v[22:25], v[162:165], v[210:213], v[22:25]
	v_mfma_f32_16x16x32_bf16 v[18:21], v[178:181], v[210:213], v[18:21]
	s_setprio 0
	s_barrier
	s_add_u32 s6, s6, 0x80080
	s_addc_u32 s7, s7, 0
	s_add_i32 s8, s50, s26
	s_mov_b32 m0, s8
	s_nop 0
	global_load_lds_dwordx4 v0, s[6:7]
	s_add_i32 m0, s8, 0x2000
	s_nop 0
	global_load_lds_dwordx4 v130, s[6:7]
	s_waitcnt vmcnt(6)
	s_barrier
	s_setprio 1
	v_mfma_f32_16x16x32_bf16 v[46:49], v[214:217], v[182:185], v[46:49]
	v_mfma_f32_16x16x32_bf16 v[42:45], v[222:225], v[182:185], v[42:45]
	v_mfma_f32_16x16x32_bf16 v[30:33], v[214:217], v[190:193], v[30:33]
	v_mfma_f32_16x16x32_bf16 v[26:29], v[222:225], v[190:193], v[26:29]
	v_mfma_f32_16x16x32_bf16 v[14:17], v[214:217], v[198:201], v[14:17]
	v_mfma_f32_16x16x32_bf16 v[10:13], v[222:225], v[198:201], v[10:13]
	v_mfma_f32_16x16x32_bf16 v[6:9], v[214:217], v[206:209], v[6:9]
	v_mfma_f32_16x16x32_bf16 v[2:5], v[222:225], v[206:209], v[2:5]
	v_mfma_f32_16x16x32_bf16 v[46:49], v[218:221], v[186:189], v[46:49]
	v_mfma_f32_16x16x32_bf16 v[42:45], v[226:229], v[186:189], v[42:45]
	v_mfma_f32_16x16x32_bf16 v[30:33], v[218:221], v[194:197], v[30:33]
	v_mfma_f32_16x16x32_bf16 v[26:29], v[226:229], v[194:197], v[26:29]
	v_mfma_f32_16x16x32_bf16 v[14:17], v[218:221], v[202:205], v[14:17]
	v_mfma_f32_16x16x32_bf16 v[10:13], v[226:229], v[202:205], v[10:13]
	v_mfma_f32_16x16x32_bf16 v[6:9], v[218:221], v[210:213], v[6:9]
	v_mfma_f32_16x16x32_bf16 v[2:5], v[226:229], v[210:213], v[2:5]
	s_setprio 0
	s_add_i32 s68, s68, 2
	s_add_u32 s4, s4, 0x100
	s_addc_u32 s5, s5, 0
	s_add_u32 s6, s44, s4
	s_addc_u32 s7, s45, s5
	s_add_u32 s8, s6, 0x100
	s_addc_u32 s9, s7, 0
	s_add_u32 s69, s66, s4
	s_addc_u32 s78, s67, s5
	s_add_u32 s86, s6, 0x180
	s_addc_u32 s87, s7, 0
	s_cmpk_eq_i32 s4, 0xf00
	s_cselect_b32 s51, s30, s9
	s_cselect_b32 s50, s31, s8
	s_cselect_b32 s7, s39, s78
	s_cselect_b32 s6, s43, s69
	s_cselect_b32 s9, s65, s87
	s_cselect_b32 s8, s64, s86
	s_add_u32 s86, s44, s4
	s_addc_u32 s87, s45, s5
	s_add_u32 s86, s86, 0x80080
	s_addc_u32 s87, s87, 0
	s_cmp_gt_u32 s68, 29
	s_barrier
	.p2align 6
